# s_setprio 3 for statically placed RWKV/HGRN chain blocks (b<192) during the recurrence phase, reset at barrier entry
# speedup vs baseline: 1.0048x; 1.0048x over previous
.LBB0_89:
	s_or_b64 exec, exec, s[6:7]
	s_waitcnt vmcnt(0)
	s_setprio 0
	s_barrier
	s_mov_b64 s[0:1], exec
	v_readlane_b32 s4, v254, 1
	v_readlane_b32 s5, v254, 2
	s_and_b64 s[4:5], s[0:1], s[4:5]
	s_mov_b64 exec, s[4:5]
	s_cbranch_execz .LBB0_141
	s_add_i32 s3, 0, 0x10000
	v_mov_b32_e32 v0, s3
	s_waitcnt vmcnt(0) expcnt(0) lgkmcnt(0)
	ds_read_b32 v2, v0
	s_add_i32 s3, 0, 0x10004
	v_mov_b32_e32 v0, s3
	ds_read_b32 v0, v0
	s_waitcnt lgkmcnt(1)
	v_cmp_ne_u32_e32 vcc, 0, v2
	s_cbranch_vccnz .LBB0_105
	s_add_u32 s4, s50, 0x1000
	s_addc_u32 s5, s51, 0
	s_add_u32 s6, s50, 0x1100
	s_addc_u32 s7, s51, 0
	s_add_u32 s8, s50, 0x1200
	v_readlane_b32 s3, v254, 0
	s_addc_u32 s9, s51, 0
	s_mul_i32 s3, s29, s3
	s_add_u32 s10, s50, 0x1300
	s_mul_i32 s3, s3, s28
	s_addc_u32 s11, s51, 0
	s_mov_b32 s34, 1
	v_mov_b32_e32 v16, 0
	s_branch .LBB0_93

.LBB0_158:
	s_waitcnt vmcnt(0)
	s_setprio 0
	s_barrier
	s_mov_b64 s[0:1], exec
	v_readlane_b32 s4, v254, 1
	v_readlane_b32 s5, v254, 2
	s_and_b64 s[4:5], s[0:1], s[4:5]
	s_mov_b64 exec, s[4:5]
	s_cbranch_execz .LBB0_210
	s_add_i32 s3, 0, 0x10000
	v_mov_b32_e32 v0, s3
	s_waitcnt vmcnt(0) expcnt(0) lgkmcnt(0)
	ds_read_b32 v2, v0
	s_add_i32 s3, 0, 0x10004
	v_mov_b32_e32 v0, s3
	ds_read_b32 v0, v0
	s_waitcnt lgkmcnt(1)
	v_cmp_ne_u32_e32 vcc, 0, v2
	s_cbranch_vccnz .LBB0_174
	s_add_u32 s4, s50, 0x1000
	s_addc_u32 s5, s51, 0
	s_add_u32 s6, s50, 0x1100
	s_addc_u32 s7, s51, 0
	s_add_u32 s8, s50, 0x1200
	v_readlane_b32 s3, v254, 0
	s_addc_u32 s9, s51, 0
	s_mul_i32 s3, s29, s3
	s_add_u32 s10, s50, 0x1300
	s_mul_i32 s3, s3, s28
	s_addc_u32 s11, s51, 0
	s_mov_b32 s34, 1
	v_mov_b32_e32 v16, 0
	s_branch .LBB0_162

.LBB0_285:
	s_or_b64 exec, exec, s[0:1]
	v_readlane_b32 s4, v254, 3
	v_readlane_b32 s18, v254, 17
	v_readlane_b32 s19, v254, 18
	s_add_u32 s0, s18, 0x5790000
	v_readlane_b32 s5, v254, 4
	v_readlane_b32 s6, v254, 5
	v_readlane_b32 s7, v254, 6
	v_readlane_b32 s8, v254, 7
	v_readlane_b32 s9, v254, 8
	v_readlane_b32 s10, v254, 9
	v_readlane_b32 s11, v254, 10
	v_readlane_b32 s12, v254, 11
	v_readlane_b32 s13, v254, 12
	v_readlane_b32 s14, v254, 13
	v_readlane_b32 s15, v254, 14
	v_readlane_b32 s16, v254, 15
	v_readlane_b32 s17, v254, 16
	v_writelane_b32 v254, s0, 62
	s_addc_u32 s0, s19, 0
	s_add_u32 s26, s74, 0x1000
	s_addc_u32 s27, s75, 0
	v_writelane_b32 v254, s0, 63
	s_add_u32 s0, s74, 0x1200
	s_addc_u32 s1, s75, 0
	s_mov_b32 s87, 0
	v_writelane_b32 v255, s0, 0
	v_mov_b32_e32 v28, 0
	s_movk_i32 s7, 0x1e20
	v_writelane_b32 v255, s1, 1
	s_add_u32 s0, s74, 0x1400
	s_addc_u32 s1, s75, 0
	v_writelane_b32 v255, s0, 2
	s_movk_i32 s24, 0x1000
	s_mov_b32 s90, 0xbfb8aa3b
	v_writelane_b32 v255, s1, 3
	s_add_u32 s0, s74, 0x1600
	s_addc_u32 s1, s75, 0
	v_writelane_b32 v255, s0, 4
	s_mov_b32 s91, 0x800000
	s_mov_b32 s92, 0x3f317217
	v_writelane_b32 v255, s1, 5
	s_add_u32 s0, s74, 0x1800
	s_addc_u32 s1, s75, 0
	v_writelane_b32 v255, s0, 6
	s_mov_b32 s93, 0x7f800000
	s_mov_b32 s6, 0x3e3504f3
	v_writelane_b32 v255, s1, 7
	s_add_u32 s0, s74, 0x1a00
	s_addc_u32 s1, s75, 0
	v_writelane_b32 v255, s0, 8
	s_movk_i32 s94, 0x800
	v_mov_b32_e32 v71, 0x42800000
	v_writelane_b32 v255, s1, 9
	s_add_u32 s0, s74, 0x1c00
	s_addc_u32 s1, s75, 0
	v_writelane_b32 v255, s0, 10
	v_mov_b32_e32 v72, 0x1800
	v_mov_b32_e32 v73, 0x1600
	v_writelane_b32 v255, s1, 11
	s_add_u32 s0, s74, 0x1e00
	s_addc_u32 s1, s75, 0
	v_writelane_b32 v255, s0, 12
	v_mov_b32_e32 v74, 0x3e000000
	v_mov_b32_e32 v75, 0x41b17218
	v_writelane_b32 v255, s1, 13
	s_add_u32 s0, s18, 0x4790000
	v_writelane_b32 v255, s0, 14
	s_addc_u32 s0, s19, 0
	v_writelane_b32 v255, s0, 15
	s_add_u32 s0, s18, 0x7090000
	v_writelane_b32 v255, s0, 16
	s_addc_u32 s0, s19, 0
	v_writelane_b32 v255, s0, 17
	s_add_u32 s0, s18, 0x5f90000
	v_writelane_b32 v255, s0, 18
	s_addc_u32 s0, s19, 0
	s_add_u32 s31, s18, 0x4690000
	v_writelane_b32 v255, s0, 19
	s_addc_u32 s0, s19, 0
	v_writelane_b32 v255, s0, 20
	s_add_u32 s0, s18, 0x4500000
	v_writelane_b32 v255, s0, 22
	s_addc_u32 s0, s19, 0
	v_writelane_b32 v255, s0, 24
	s_add_u32 s0, s18, 0x4400000
	v_writelane_b32 v255, s0, 26
	s_addc_u32 s0, s19, 0
	v_writelane_b32 v255, s0, 42
	s_add_i32 s3, 0, 0x10010
	s_add_i32 s0, 0, 0x3000
	v_writelane_b32 v255, s0, 44
	v_mov_b32_e32 v70, s3
	v_mov_b32_e32 v76, 0xc00
	v_mov_b32_e32 v77, 0xb00
	v_mov_b32_e32 v78, 0x1000
	s_waitcnt lgkmcnt(0)
	s_barrier
	s_mov_b32 s99, -1
	s_mov_b32 s100, 0
	s_cmp_lg_u32 s28, 0x200
	s_cbranch_scc1 .Lmap_done_0
	s_movk_i32 s100, 0x140
	s_cmp_ge_u32 s2, 0x100
	s_cbranch_scc1 .Lmap_hi_0
	s_mov_b32 s99, s2
	s_cmp_ge_u32 s2, 192
	s_cbranch_scc1 .Lmap_np_0
	s_setprio 3
.Lmap_np_0:
	s_cmp_lt_u32 s2, 192
	s_cbranch_scc1 .Lmap_done_0
	s_add_u32 s99, s2, 64
	s_branch .Lmap_done_0

.LBB0_817:
	s_or_b64 exec, exec, s[4:5]
	s_waitcnt vmcnt(0)
	s_setprio 0
	s_barrier
	s_mov_b64 s[0:1], exec
	v_readlane_b32 s4, v254, 1
	v_readlane_b32 s5, v254, 2
	s_and_b64 s[4:5], s[0:1], s[4:5]
	s_mov_b64 exec, s[4:5]
	s_cbranch_execz .LBB0_869
	s_add_i32 s3, 0, 0x10000
	v_mov_b32_e32 v0, s3
	s_waitcnt vmcnt(0) expcnt(0) lgkmcnt(0)
	ds_read_b32 v2, v0
	s_add_i32 s3, 0, 0x10004
	v_mov_b32_e32 v0, s3
	ds_read_b32 v0, v0
	s_waitcnt lgkmcnt(1)
	v_cmp_ne_u32_e32 vcc, 0, v2
	s_cbranch_vccnz .LBB0_833
	s_add_u32 s4, s50, 0x1000
	s_addc_u32 s5, s51, 0
	s_add_u32 s6, s50, 0x1100
	s_addc_u32 s7, s51, 0
	s_add_u32 s8, s50, 0x1200
	v_readlane_b32 s3, v254, 0
	s_addc_u32 s9, s51, 0
	s_mul_i32 s3, s29, s3
	s_add_u32 s10, s50, 0x1300
	s_mul_i32 s3, s3, s28
	s_addc_u32 s11, s51, 0
	s_mov_b32 s34, 1
	v_mov_b32_e32 v16, 0
	s_branch .LBB0_821

.LBB0_955:
	s_waitcnt vmcnt(0)
	s_setprio 0
	s_barrier
	s_mov_b64 s[0:1], exec
	v_readlane_b32 s4, v254, 1
	v_readlane_b32 s5, v254, 2
	v_writelane_b32 v254, s96, 56
	s_and_b64 s[4:5], s[0:1], s[4:5]
	s_nop 0
	v_writelane_b32 v254, s97, 57
	s_mov_b64 exec, s[4:5]
	s_cbranch_execz .LBB0_1007
	s_add_i32 s3, 0, 0x10000
	v_mov_b32_e32 v0, s3
	s_waitcnt vmcnt(0) expcnt(0) lgkmcnt(0)
	ds_read_b32 v2, v0
	s_add_i32 s3, 0, 0x10004
	v_mov_b32_e32 v0, s3
	ds_read_b32 v0, v0
	s_waitcnt lgkmcnt(1)
	v_cmp_ne_u32_e32 vcc, 0, v2
	s_cbranch_vccnz .LBB0_971
	s_add_u32 s4, s50, 0x1000
	s_addc_u32 s5, s51, 0
	s_add_u32 s6, s50, 0x1100
	s_addc_u32 s7, s51, 0
	s_add_u32 s8, s50, 0x1200
	v_readlane_b32 s3, v254, 0
	s_addc_u32 s9, s51, 0
	s_mul_i32 s3, s29, s3
	s_add_u32 s10, s50, 0x1300
	s_mul_i32 s3, s3, s28
	s_addc_u32 s11, s51, 0
	s_mov_b32 s34, 1
	v_mov_b32_e32 v16, 0
	s_branch .LBB0_959

.LBB0_1075:
	s_or_b64 exec, exec, s[4:5]
	s_waitcnt vmcnt(0)
	s_setprio 0
	s_barrier
	s_mov_b64 s[0:1], exec
	v_readlane_b32 s4, v254, 1
	v_readlane_b32 s5, v254, 2
	s_and_b64 s[4:5], s[0:1], s[4:5]
	s_mov_b64 exec, s[4:5]
	s_cbranch_execz .LBB0_1127
	s_add_i32 s3, 0, 0x10000
	v_mov_b32_e32 v0, s3
	s_waitcnt vmcnt(0) expcnt(0) lgkmcnt(0)
	ds_read_b32 v2, v0
	s_add_i32 s3, 0, 0x10004
	v_mov_b32_e32 v0, s3
	ds_read_b32 v0, v0
	s_waitcnt lgkmcnt(1)
	v_cmp_ne_u32_e32 vcc, 0, v2
	s_cbranch_vccnz .LBB0_1091
	s_add_u32 s4, s50, 0x1000
	s_addc_u32 s5, s51, 0
	s_add_u32 s6, s50, 0x1100
	s_addc_u32 s7, s51, 0
	s_add_u32 s8, s50, 0x1200
	v_readlane_b32 s3, v254, 0
	s_addc_u32 s9, s51, 0
	s_mul_i32 s3, s29, s3
	s_add_u32 s10, s50, 0x1300
	s_mul_i32 s3, s3, s28
	s_addc_u32 s11, s51, 0
	s_mov_b32 s24, 1
	v_mov_b32_e32 v16, 0
	s_branch .LBB0_1079

.LBB0_1144:
	s_waitcnt vmcnt(0)
	s_setprio 0
	s_barrier
	s_mov_b64 s[0:1], exec
	v_readlane_b32 s4, v254, 1
	v_readlane_b32 s5, v254, 2
	s_and_b64 s[4:5], s[0:1], s[4:5]
	s_mov_b64 exec, s[4:5]
	s_cbranch_execz .LBB0_1196
	s_add_i32 s3, 0, 0x10000
	v_mov_b32_e32 v0, s3
	s_waitcnt vmcnt(0) expcnt(0) lgkmcnt(0)
	ds_read_b32 v2, v0
	s_add_i32 s3, 0, 0x10004
	v_mov_b32_e32 v0, s3
	ds_read_b32 v0, v0
	s_waitcnt lgkmcnt(1)
	v_cmp_ne_u32_e32 vcc, 0, v2
	s_cbranch_vccnz .LBB0_1160
	s_add_u32 s4, s50, 0x1000
	s_addc_u32 s5, s51, 0
	s_add_u32 s6, s50, 0x1100
	s_addc_u32 s7, s51, 0
	s_add_u32 s8, s50, 0x1200
	v_readlane_b32 s3, v254, 0
	s_addc_u32 s9, s51, 0
	s_mul_i32 s3, s29, s3
	s_add_u32 s10, s50, 0x1300
	s_mul_i32 s3, s3, s28
	s_addc_u32 s11, s51, 0
	s_mov_b32 s24, 1
	v_mov_b32_e32 v16, 0
	s_branch .LBB0_1148

.LBB0_1216:
	s_waitcnt vmcnt(0)
	s_setprio 0
	s_barrier
	s_mov_b64 s[0:1], exec
	v_readlane_b32 s4, v254, 1
	v_readlane_b32 s5, v254, 2
	s_and_b64 s[4:5], s[0:1], s[4:5]
	s_mov_b64 exec, s[4:5]
	s_cbranch_execz .LBB0_1268
	s_add_i32 s3, 0, 0x10000
	v_mov_b32_e32 v0, s3
	s_waitcnt vmcnt(0) expcnt(0) lgkmcnt(0)
	ds_read_b32 v2, v0
	s_add_i32 s3, 0, 0x10004
	v_mov_b32_e32 v0, s3
	ds_read_b32 v0, v0
	s_waitcnt lgkmcnt(1)
	v_cmp_ne_u32_e32 vcc, 0, v2
	s_cbranch_vccnz .LBB0_1232
	s_add_u32 s4, s50, 0x1000
	s_addc_u32 s5, s51, 0
	s_add_u32 s6, s50, 0x1100
	s_addc_u32 s7, s51, 0
	s_add_u32 s8, s50, 0x1200
	v_readlane_b32 s3, v254, 0
	s_addc_u32 s9, s51, 0
	s_mul_i32 s3, s29, s3
	s_add_u32 s10, s50, 0x1300
	s_mul_i32 s3, s3, s28
	s_addc_u32 s11, s51, 0
	s_mov_b32 s26, 1
	v_mov_b32_e32 v16, 0
	s_branch .LBB0_1220

.LBB0_1268:
	s_or_b64 exec, exec, s[0:1]
	v_readlane_b32 s52, v255, 26
	v_readlane_b32 s58, v255, 32
	v_readlane_b32 s59, v255, 33
	s_add_u32 s92, s58, 0x2000
	s_addc_u32 s93, s59, 0
	s_add_u32 s0, s58, 0x3000
	s_addc_u32 s1, s59, 0
	v_writelane_b32 v254, s0, 37
	v_readlane_b32 s53, v255, 27
	v_readlane_b32 s54, v255, 28
	v_writelane_b32 v254, s1, 38
	s_add_u32 s0, s58, 0x2200
	s_addc_u32 s1, s59, 0
	v_writelane_b32 v254, s0, 58
	v_readlane_b32 s55, v255, 29
	v_readlane_b32 s56, v255, 30
	v_writelane_b32 v254, s1, 59
	s_add_u32 s0, s58, 0x3200
	s_addc_u32 s1, s59, 0
	v_readlane_b32 s57, v255, 31
	v_readlane_b32 s60, v255, 34
	v_readlane_b32 s61, v255, 35
	v_readlane_b32 s62, v255, 36
	v_readlane_b32 s63, v255, 37
	v_readlane_b32 s64, v255, 38
	v_readlane_b32 s65, v255, 39
	v_readlane_b32 s66, v255, 40
	v_readlane_b32 s67, v255, 41
	v_writelane_b32 v255, s0, 20
	s_mov_b32 s11, 0
	v_mov_b32_e32 v28, 0
	v_writelane_b32 v255, s1, 21
	s_add_u32 s0, s58, 0x2400
	s_addc_u32 s1, s59, 0
	v_writelane_b32 v255, s0, 22
	s_movk_i32 s3, 0x1e20
	s_movk_i32 s94, 0x1000
	v_writelane_b32 v255, s1, 23
	s_add_u32 s0, s58, 0x3400
	s_addc_u32 s1, s59, 0
	v_writelane_b32 v255, s0, 24
	s_mov_b32 s95, 0xbfb8aa3b
	s_mov_b32 s52, 0x800000
	v_writelane_b32 v255, s1, 25
	s_add_u32 s0, s58, 0x2600
	s_addc_u32 s1, s59, 0
	v_writelane_b32 v254, s0, 60
	s_mov_b32 s53, 0x3f317217
	s_mov_b32 s54, 0x7f800000
	v_writelane_b32 v254, s1, 61
	s_add_u32 s0, s58, 0x3600
	s_addc_u32 s1, s59, 0
	v_writelane_b32 v255, s0, 0
	s_mov_b32 s4, 0x3e3504f3
	s_movk_i32 s55, 0x800
	v_writelane_b32 v255, s1, 1
	s_add_u32 s0, s58, 0x2800
	s_addc_u32 s1, s59, 0
	v_writelane_b32 v255, s0, 2
	v_mov_b32_e32 v73, 0x42800000
	v_mov_b32_e32 v74, 0x1800
	v_writelane_b32 v255, s1, 3
	s_add_u32 s0, s58, 0x3800
	s_addc_u32 s1, s59, 0
	v_writelane_b32 v255, s0, 4
	v_mov_b32_e32 v75, 0x1600
	v_mov_b32_e32 v76, 0x3e000000
	v_writelane_b32 v255, s1, 5
	s_add_u32 s0, s58, 0x2a00
	s_addc_u32 s1, s59, 0
	v_writelane_b32 v255, s0, 6
	v_mov_b32_e32 v77, 0x41b17218
	v_mov_b32_e32 v78, 0xc00
	v_writelane_b32 v255, s1, 7
	s_add_u32 s0, s58, 0x3a00
	s_addc_u32 s1, s59, 0
	v_writelane_b32 v255, s0, 8
	v_mov_b32_e32 v79, 0xb00
	v_mov_b32_e32 v80, 0x1000
	v_writelane_b32 v255, s1, 9
	s_add_u32 s0, s58, 0x2c00
	s_addc_u32 s1, s59, 0
	v_writelane_b32 v255, s0, 10
	s_waitcnt lgkmcnt(0)
	s_barrier
	v_writelane_b32 v255, s1, 11
	s_add_u32 s0, s58, 0x3c00
	s_addc_u32 s1, s59, 0
	s_add_u32 s96, s58, 0x2e00
	s_addc_u32 s97, s59, 0
	s_add_u32 s90, s58, 0x3e00
	v_writelane_b32 v255, s0, 12
	s_addc_u32 s91, s59, 0
	s_add_i32 s5, 0, 0x10010
	v_writelane_b32 v255, s1, 13
	v_mov_b32_e32 v72, s5
	s_mov_b32 s99, -1
	s_mov_b32 s100, 0
	s_cmp_lg_u32 s28, 0x200
	s_cbranch_scc1 .Lmap_done_1
	s_movk_i32 s100, 0x140
	s_cmp_ge_u32 s2, 0x100
	s_cbranch_scc1 .Lmap_hi_1
	s_mov_b32 s99, s2
	s_cmp_ge_u32 s2, 192
	s_cbranch_scc1 .Lmap_np_1
	s_setprio 3

.LBB0_1458:
	s_waitcnt vmcnt(0)
	s_setprio 0
	s_barrier
	s_mov_b64 s[0:1], exec
	v_readlane_b32 s4, v254, 1
	v_readlane_b32 s5, v254, 2
	v_readlane_b32 s68, v254, 56
	s_and_b64 s[4:5], s[0:1], s[4:5]
	v_readlane_b32 s69, v254, 57
	s_mov_b64 exec, s[4:5]
	s_cbranch_execz .LBB0_1510
	s_add_i32 s3, 0, 0x10000
	v_mov_b32_e32 v0, s3
	s_waitcnt vmcnt(0) expcnt(0) lgkmcnt(0)
	ds_read_b32 v2, v0
	s_add_i32 s3, 0, 0x10004
	v_mov_b32_e32 v0, s3
	ds_read_b32 v0, v0
	s_waitcnt lgkmcnt(1)
	v_cmp_ne_u32_e32 vcc, 0, v2
	s_cbranch_vccnz .LBB0_1474
	s_add_u32 s4, s50, 0x1000
	s_addc_u32 s5, s51, 0
	s_add_u32 s6, s50, 0x1100
	s_addc_u32 s7, s51, 0
	s_add_u32 s8, s50, 0x1200
	v_readlane_b32 s3, v254, 0
	s_addc_u32 s9, s51, 0
	s_mul_i32 s3, s29, s3
	s_add_u32 s10, s50, 0x1300
	s_mul_i32 s3, s3, s28
	s_addc_u32 s11, s51, 0
	s_mov_b32 s26, 1
	v_mov_b32_e32 v16, 0
	s_branch .LBB0_1462

.LBB0_1526:
	s_waitcnt vmcnt(0)
	s_setprio 0
	s_barrier
	s_mov_b64 s[0:1], exec
	v_readlane_b32 s4, v254, 1
	v_readlane_b32 s5, v254, 2
	v_readlane_b32 s30, v255, 42
	s_and_b64 s[4:5], s[0:1], s[4:5]
	v_readlane_b32 s31, v255, 43
	s_mov_b64 exec, s[4:5]
	s_cbranch_execz .LBB0_1578
	s_add_i32 s3, 0, 0x10000
	v_mov_b32_e32 v0, s3
	s_waitcnt vmcnt(0) expcnt(0) lgkmcnt(0)
	ds_read_b32 v2, v0
	s_add_i32 s3, 0, 0x10004
	v_mov_b32_e32 v0, s3
	ds_read_b32 v0, v0
	s_waitcnt lgkmcnt(1)
	v_cmp_ne_u32_e32 vcc, 0, v2
	s_cbranch_vccnz .LBB0_1542
	s_add_u32 s4, s50, 0x1000
	s_addc_u32 s5, s51, 0
	s_add_u32 s6, s50, 0x1100
	s_addc_u32 s7, s51, 0
	s_add_u32 s8, s50, 0x1200
	v_readlane_b32 s3, v254, 0
	s_addc_u32 s9, s51, 0
	s_mul_i32 s3, s29, s3
	s_add_u32 s10, s50, 0x1300
	s_mul_i32 s3, s3, s28
	s_addc_u32 s11, s51, 0
	s_mov_b32 s20, 1
	v_mov_b32_e32 v16, 0
	s_branch .LBB0_1530

.LBB0_1595:
	s_waitcnt vmcnt(0)
	s_setprio 0
	s_barrier
	s_mov_b64 s[0:1], exec
	v_readlane_b32 s4, v254, 1
	v_readlane_b32 s5, v254, 2
	s_and_b64 s[4:5], s[0:1], s[4:5]
	s_mov_b64 exec, s[4:5]
	s_cbranch_execz .LBB0_1647
	s_add_i32 s3, 0, 0x10000
	v_mov_b32_e32 v0, s3
	s_waitcnt vmcnt(0) expcnt(0) lgkmcnt(0)
	ds_read_b32 v2, v0
	s_add_i32 s3, 0, 0x10004
	v_mov_b32_e32 v0, s3
	ds_read_b32 v0, v0
	s_waitcnt lgkmcnt(1)
	v_cmp_ne_u32_e32 vcc, 0, v2
	s_cbranch_vccnz .LBB0_1611
	s_add_u32 s4, s50, 0x1000
	s_addc_u32 s5, s51, 0
	s_add_u32 s6, s50, 0x1100
	s_addc_u32 s7, s51, 0
	s_add_u32 s8, s50, 0x1200
	v_readlane_b32 s3, v254, 0
	s_addc_u32 s9, s51, 0
	s_mul_i32 s3, s29, s3
	s_add_u32 s10, s50, 0x1300
	s_mul_i32 s3, s3, s28
	s_addc_u32 s11, s51, 0
	s_mov_b32 s20, 1
	v_mov_b32_e32 v16, 0
	s_branch .LBB0_1599

.LBB0_1800:
	s_or_b64 exec, exec, s[4:5]
	s_waitcnt vmcnt(0)
	s_setprio 0
	s_barrier
	s_mov_b64 s[0:1], exec
	v_readlane_b32 s4, v254, 1
	v_readlane_b32 s5, v254, 2
	s_and_b64 s[4:5], s[0:1], s[4:5]
	s_mov_b64 exec, s[4:5]
	s_cbranch_execz .LBB0_1852
	s_add_i32 s3, 0, 0x10000
	v_mov_b32_e32 v0, s3
	s_waitcnt vmcnt(0) expcnt(0) lgkmcnt(0)
	ds_read_b32 v2, v0
	s_add_i32 s3, 0, 0x10004
	v_mov_b32_e32 v0, s3
	ds_read_b32 v0, v0
	s_waitcnt lgkmcnt(1)
	v_cmp_ne_u32_e32 vcc, 0, v2
	s_cbranch_vccnz .LBB0_1816
	s_add_u32 s4, s50, 0x1000
	s_addc_u32 s5, s51, 0
	s_add_u32 s6, s50, 0x1100
	s_addc_u32 s7, s51, 0
	s_add_u32 s8, s50, 0x1200
	v_readlane_b32 s3, v254, 0
	s_addc_u32 s9, s51, 0
	s_mul_i32 s3, s29, s3
	s_add_u32 s10, s50, 0x1300
	s_mul_i32 s3, s3, s28
	s_addc_u32 s11, s51, 0
	s_mov_b32 s20, 1
	v_mov_b32_e32 v16, 0
	s_branch .LBB0_1804

.LBB0_1938:
	s_waitcnt vmcnt(0)
	s_setprio 0
	s_barrier
	s_mov_b64 s[0:1], exec
	v_readlane_b32 s2, v254, 1
	v_readlane_b32 s3, v254, 2
	s_and_b64 s[2:3], s[0:1], s[2:3]
	s_mov_b64 exec, s[2:3]
	s_cbranch_execz .LBB0_1990
	s_add_i32 s2, 0, 0x10000
	v_mov_b32_e32 v0, s2
	s_waitcnt vmcnt(0) expcnt(0) lgkmcnt(0)
	ds_read_b32 v2, v0
	s_add_i32 s2, 0, 0x10004
	v_mov_b32_e32 v0, s2
	ds_read_b32 v0, v0
	s_waitcnt lgkmcnt(1)
	v_cmp_ne_u32_e32 vcc, 0, v2
	s_cbranch_vccnz .LBB0_1954
	v_readlane_b32 s2, v254, 0
	s_mul_i32 s15, s29, s2
	s_add_u32 s2, s50, 0x1000
	s_addc_u32 s3, s51, 0
	s_add_u32 s4, s50, 0x1100
	s_addc_u32 s5, s51, 0
	s_add_u32 s6, s50, 0x1200
	s_addc_u32 s7, s51, 0
	s_add_u32 s8, s50, 0x1300
	s_mul_i32 s15, s15, s28
	s_addc_u32 s9, s51, 0
	s_mov_b32 s18, 1
	v_mov_b32_e32 v16, 0
	s_branch .LBB0_1942
